# first phase seam uses the counter grid barrier instead of cooperative-groups grid sync
# speedup vs baseline: 1.0402x; 1.0006x over previous
; DI void fast_grid_barrier(unsigned* ctr, unsigned target) {
;     asm volatile("s_waitcnt vmcnt(0)" ::: "memory");
;     __syncthreads();
;     if (threadIdx.x == 0) {
;         __builtin_amdgcn_fence(__ATOMIC_RELEASE, "agent");
;         asm volatile("s_waitcnt vmcnt(0)" ::: "memory");
;         __hip_atomic_fetch_add(ctr, 1u, __ATOMIC_RELAXED, __HIP_MEMORY_SCOPE_AGENT);
;         while (__hip_atomic_load(ctr, __ATOMIC_RELAXED, __HIP_MEMORY_SCOPE_AGENT) < target) __builtin_amdgcn_s_sleep(1);
; __global__ void __launch_bounds__(512, 2) mega_fwd(Params p) {
;     ...
;         if (phx > p.ph_lo * (1 + REP_N)) {
;             if (phx == p.ph_lo * (1 + REP_N) + 1) cg::this_grid().sync();
;             else { ++nbar; fast_grid_barrier((unsigned*)(p.ws + OFF_CTR), nbar * (unsigned)G0); }
.LBB0_4:
	s_cmp_le_i32 s70, s12
	s_cbranch_scc1 .LBB0_26
	v_readlane_b32 s0, v255, 4
	s_cmp_lg_u32 s70, s0
	s_mov_b64 s[0:1], -1
	s_waitcnt vmcnt(0)
	v_readlane_b32 s0, v255, 11
	s_add_i32 s4, s0, 1
	s_barrier
	s_mov_b64 s[0:1], exec
	v_readlane_b32 s6, v255, 12
	v_readlane_b32 s7, v255, 13
	s_and_b64 s[6:7], s[0:1], s[6:7]
	s_mov_b64 exec, s[6:7]
	s_cbranch_execz .LBB0_12
	s_mov_b64 s[6:7], exec
	buffer_wbl2 sc1
	s_waitcnt vmcnt(0)
	v_mbcnt_lo_u32_b32 v0, s6, 0
	v_mbcnt_hi_u32_b32 v0, s7, v0
	v_cmp_eq_u32_e32 vcc, 0, v0
	s_and_saveexec_b64 s[8:9], vcc
	s_cbranch_execz .LBB0_9
	s_bcnt1_i32_b64 s5, s[6:7]
	v_mov_b32_e32 v0, s5
	global_atomic_add v165, v0, s[14:15]

; DI void fast_grid_barrier(unsigned* ctr, unsigned target) {
;     ...
;         __builtin_amdgcn_fence(__ATOMIC_ACQUIRE, "agent");
;         asm volatile("s_waitcnt vmcnt(0)" ::: "memory");
;     }
;     __syncthreads();
; __global__ void __launch_bounds__(512, 2) mega_fwd(Params p) {
;     ...
;             if (phx == p.ph_lo * (1 + REP_N) + 1) cg::this_grid().sync();
;             else { ++nbar; fast_grid_barrier((unsigned*)(p.ws + OFF_CTR), nbar * (unsigned)G0); }
.LBB0_12:
	s_or_b64 exec, exec, s[0:1]
	s_mov_b64 s[0:1], 0
	s_barrier
.LBB0_25:
	s_nop 0
	v_writelane_b32 v255, s4, 11
